# pass2 Y 16-B stores write-through (sc1) so the grid barrier's L2 write-back finds fewer dirty lines
# speedup vs baseline: 1.0095x; 1.0095x over previous
.LBB0_168:
	s_or_b64 exec, exec, s[4:5]
	v_lshl_add_u64 v[88:89], v[30:31], 0, v[90:91]
	global_load_dwordx4 v[78:81], v[88:89], off
	global_load_dwordx4 v[82:85], v[88:89], off offset:64
	global_load_dwordx4 v[16:19], v[32:33], off offset:192
	global_load_dwordx4 v[20:23], v[32:33], off offset:128
	global_load_dwordx4 v[24:27], v[32:33], off offset:64
	global_load_dwordx4 v[52:55], v[32:33], off
	s_waitcnt lgkmcnt(0)
	v_add_f32_e32 v30, v50, v51
	v_mov_b32_e32 v31, 0x3727c5ac
	v_fmamk_f32 v30, v30, 0x3c800000, v31
	s_mov_b32 s4, 0x800000
	v_cmp_gt_f32_e32 vcc, s4, v30
	v_mul_f32_e32 v31, 0x4b800000, v30
	v_mov_b64_e32 v[32:33], s[68:69]
	s_movk_i32 s8, 0x600
	v_cndmask_b32_e32 v30, v30, v31, vcc
	v_mad_u64_u32 v[32:33], s[4:5], v40, s8, v[32:33]
	v_rsq_f32_e32 v30, v30
	v_mov_b32_e32 v40, v33
	v_mad_u64_u32 v[40:41], s[4:5], v41, s8, v[40:41]
	v_mov_b32_e32 v33, v40
	v_lshl_add_u64 v[32:33], v[32:33], 0, v[44:45]
	v_mul_f32_e32 v31, 0x45800000, v30
	v_lshl_add_u64 v[32:33], v[36:37], 1, v[32:33]
	v_cndmask_b32_e32 v30, v30, v31, vcc
	v_add_u32_e32 v46, s2, v46
	s_movk_i32 s4, 0x1fff
	v_cmp_lt_i32_e32 vcc, s4, v46
	s_movk_i32 s67, 0x600
	v_add_u32_e32 v47, s3, v47
	v_add_u32_e32 v48, s6, v48
	v_add_u32_e32 v49, s7, v49
	s_or_b64 s[84:85], vcc, s[84:85]
	s_waitcnt vmcnt(0)
	v_permlane16_swap_b32_e32 v78, v80
	v_permlane16_swap_b32_e32 v79, v81
	v_permlane16_swap_b32_e32 v82, v84
	v_permlane16_swap_b32_e32 v83, v85
	s_nop 1
	v_lshlrev_b32_e32 v36, 16, v78
	v_mul_f32_e32 v31, 0xbfb8aa3b, v36
	v_exp_f32_e32 v31, v31
	v_and_b32_e32 v37, 0xffff0000, v78
	v_add_f32_e32 v31, 1.0, v31
	v_rcp_f32_e32 v40, v31
	v_pk_mul_f32 v[12:13], v[12:13], v[30:31] op_sel_hi:[1,0]
	v_mul_f32_e32 v31, 0xbfb8aa3b, v37
	v_exp_f32_e32 v31, v31
	v_pk_mul_f32 v[12:13], v[52:53], v[12:13]
	v_add_f32_e32 v31, 1.0, v31
	v_rcp_f32_e32 v41, v31
	s_nop 0
	v_pk_mul_f32 v[36:37], v[40:41], v[36:37]
	s_nop 0
	v_pk_mul_f32 v[12:13], v[36:37], v[12:13]
	s_nop 0
	v_cvt_pk_bf16_f32 v36, v12, v13
	v_lshlrev_b32_e32 v12, 16, v79
	v_mul_f32_e32 v31, 0xbfb8aa3b, v12
	v_exp_f32_e32 v31, v31
	v_and_b32_e32 v13, 0xffff0000, v79
	v_add_f32_e32 v31, 1.0, v31
	v_rcp_f32_e32 v40, v31
	v_pk_mul_f32 v[14:15], v[14:15], v[30:31] op_sel_hi:[1,0]
	v_mul_f32_e32 v31, 0xbfb8aa3b, v13
	v_exp_f32_e32 v31, v31
	v_pk_mul_f32 v[14:15], v[54:55], v[14:15]
	v_add_f32_e32 v31, 1.0, v31
	v_rcp_f32_e32 v41, v31
	v_pk_mul_f32 v[8:9], v[8:9], v[30:31] op_sel_hi:[1,0]
	v_pk_mul_f32 v[10:11], v[10:11], v[30:31] op_sel_hi:[1,0]
	v_pk_mul_f32 v[8:9], v[24:25], v[8:9]
	v_pk_mul_f32 v[12:13], v[40:41], v[12:13]
	v_pk_mul_f32 v[10:11], v[26:27], v[10:11]
	v_pk_mul_f32 v[12:13], v[12:13], v[14:15]
	v_lshlrev_b32_e32 v14, 16, v80
	v_and_b32_e32 v15, 0xffff0000, v80
	v_cvt_pk_bf16_f32 v37, v12, v13
	v_lshl_add_u64 v[12:13], v[28:29], 1, v[32:33]
	v_lshl_add_u64 v[86:87], v[12:13], 0, v[90:91]
	v_mul_f32_e32 v28, 0xbfb8aa3b, v14
	v_mul_f32_e32 v24, 0xbfb8aa3b, v15
	v_exp_f32_e32 v28, v28
	v_exp_f32_e32 v24, v24
	v_pk_mul_f32 v[4:5], v[4:5], v[30:31] op_sel_hi:[1,0]
	v_pk_mul_f32 v[6:7], v[6:7], v[30:31] op_sel_hi:[1,0]
	v_add_f32_e32 v28, 1.0, v28
	v_add_f32_e32 v24, 1.0, v24
	v_rcp_f32_e32 v28, v28
	v_rcp_f32_e32 v29, v24
	v_pk_mul_f32 v[4:5], v[20:21], v[4:5]
	v_pk_mul_f32 v[6:7], v[22:23], v[6:7]
	v_pk_mul_f32 v[0:1], v[0:1], v[30:31] op_sel_hi:[1,0]
	v_pk_mul_f32 v[14:15], v[28:29], v[14:15]
	v_pk_mul_f32 v[0:1], v[16:17], v[0:1]
	v_pk_mul_f32 v[8:9], v[14:15], v[8:9]
	v_lshlrev_b32_e32 v14, 16, v81
	v_cvt_pk_bf16_f32 v8, v8, v9
	v_mul_f32_e32 v9, 0xbfb8aa3b, v14
	v_exp_f32_e32 v9, v9
	v_and_b32_e32 v15, 0xffff0000, v81
	v_pk_mul_f32 v[2:3], v[2:3], v[30:31] op_sel_hi:[1,0]
	v_add_f32_e32 v9, 1.0, v9
	v_rcp_f32_e32 v24, v9
	v_mul_f32_e32 v9, 0xbfb8aa3b, v15
	v_exp_f32_e32 v9, v9
	v_pk_mul_f32 v[2:3], v[18:19], v[2:3]
	v_add_f32_e32 v9, 1.0, v9
	v_rcp_f32_e32 v25, v9
	s_nop 0
	v_pk_mul_f32 v[14:15], v[24:25], v[14:15]
	s_nop 0
	v_pk_mul_f32 v[10:11], v[14:15], v[10:11]
	s_nop 0
	v_cvt_pk_bf16_f32 v9, v10, v11
	v_mov_b32_e32 v70, v36
	v_mov_b32_e32 v71, v37
	v_mov_b32_e32 v72, v8
	v_mov_b32_e32 v73, v9
	s_nop 1
	v_permlane16_swap_b32_e32 v70, v72
	v_permlane16_swap_b32_e32 v71, v73
	s_nop 1
	global_store_dwordx4 v[86:87], v[70:73], off sc1
	v_lshlrev_b32_e32 v8, 16, v82
	v_and_b32_e32 v9, 0xffff0000, v82
	v_mul_f32_e32 v10, 0xbfb8aa3b, v8
	v_mul_f32_e32 v11, 0xbfb8aa3b, v9
	v_exp_f32_e32 v10, v10
	v_exp_f32_e32 v11, v11
	v_add_f32_e32 v10, 1.0, v10
	v_add_f32_e32 v11, 1.0, v11
	v_rcp_f32_e32 v10, v10
	v_rcp_f32_e32 v11, v11
	s_nop 0
	v_pk_mul_f32 v[8:9], v[10:11], v[8:9]
	s_nop 0
	v_pk_mul_f32 v[4:5], v[8:9], v[4:5]
	v_lshlrev_b32_e32 v8, 16, v83
	v_cvt_pk_bf16_f32 v4, v4, v5
	v_mul_f32_e32 v5, 0xbfb8aa3b, v8
	v_exp_f32_e32 v5, v5
	v_and_b32_e32 v9, 0xffff0000, v83
	v_add_f32_e32 v5, 1.0, v5
	v_rcp_f32_e32 v10, v5
	v_mul_f32_e32 v5, 0xbfb8aa3b, v9
	v_exp_f32_e32 v5, v5
	s_nop 0
	v_add_f32_e32 v5, 1.0, v5
	v_rcp_f32_e32 v11, v5
	s_nop 0
	v_pk_mul_f32 v[8:9], v[10:11], v[8:9]
	s_nop 0
	v_pk_mul_f32 v[6:7], v[8:9], v[6:7]
	s_nop 0
	v_cvt_pk_bf16_f32 v5, v6, v7
	v_mov_b32_e32 v74, v4
	v_mov_b32_e32 v75, v5
	v_lshlrev_b32_e32 v4, 16, v84
	v_and_b32_e32 v5, 0xffff0000, v84
	v_mul_f32_e32 v6, 0xbfb8aa3b, v4
	v_mul_f32_e32 v7, 0xbfb8aa3b, v5
	v_exp_f32_e32 v6, v6
	v_exp_f32_e32 v7, v7
	v_add_f32_e32 v6, 1.0, v6
	v_add_f32_e32 v7, 1.0, v7
	v_rcp_f32_e32 v6, v6
	v_rcp_f32_e32 v7, v7
	s_nop 0
	v_pk_mul_f32 v[4:5], v[6:7], v[4:5]
	s_nop 0
	v_pk_mul_f32 v[0:1], v[4:5], v[0:1]
	v_lshlrev_b32_e32 v4, 16, v85
	v_cvt_pk_bf16_f32 v0, v0, v1
	v_mul_f32_e32 v1, 0xbfb8aa3b, v4
	v_exp_f32_e32 v1, v1
	v_and_b32_e32 v5, 0xffff0000, v85
	v_add_f32_e32 v1, 1.0, v1
	v_rcp_f32_e32 v6, v1
	v_mul_f32_e32 v1, 0xbfb8aa3b, v5
	v_exp_f32_e32 v1, v1
	s_nop 0
	v_add_f32_e32 v1, 1.0, v1
	v_rcp_f32_e32 v7, v1
	s_nop 0
	v_pk_mul_f32 v[4:5], v[6:7], v[4:5]
	s_nop 0
	v_pk_mul_f32 v[2:3], v[4:5], v[2:3]
	s_nop 0
	v_cvt_pk_bf16_f32 v1, v2, v3
	v_mov_b32_e32 v76, v0
	v_mov_b32_e32 v77, v1
	s_nop 1
	v_permlane16_swap_b32_e32 v74, v76
	v_permlane16_swap_b32_e32 v75, v77
	s_nop 1
	global_store_dwordx4 v[86:87], v[74:77], off offset:64 sc1
	s_andn2_b64 exec, exec, s[84:85]
	s_cbranch_execz .LBB0_173
